# nt hint also on the final phase's output stores and on the per-row phase's one-use GQA head / value loads
# speedup vs baseline: 1.0155x; 1.0040x over previous
.Lrw_entry:
	v_ashrrev_i32_e32 v9, 6, v84
	v_and_b32_e32 v10, 63, v84
	v_and_b32_e32 v8, 31, v84
	s_waitcnt vmcnt(0)
	s_mov_b64 s[20:21], exec
	s_mov_b32 s22, -1
	s_mov_b32 s23, 0xffff
	s_mov_b32 s26, 0
	s_mov_b32 s27, 0xffff0000
	s_mov_b32 s76, 0xffff
	s_mov_b32 s77, 0
	s_mov_b32 s78, 0xffffff
	s_mov_b32 s79, 0
	s_mov_b32 s80, 1
	s_mov_b32 s81, 0
	s_mov_b32 s6, 0
	s_cmp_lg_u64 s[90:91], 0
	s_cselect_b32 s6, 1, 0
	s_add_u32 s82, s50, 0x1076000
	s_addc_u32 s83, s51, 0
	s_add_u32 s98, s50, 0x1079000
	s_addc_u32 s99, s51, 0
	v_and_b32_e32 v160, 63, v143
	v_lshrrev_b32_e32 v161, 3, v160
	v_and_b32_e32 v162, 7, v160
	v_lshlrev_b32_e32 v163, 4, v162
	v_cmp_gt_u32_e64 s[100:101], 4, v162
	v_cmp_gt_u32_e32 vcc, 6, v161
	v_lshl_add_u32 v196, v161, 7, v163
	v_mov_b32_e32 v164, 64
	v_mov_b32_e32 v165, 0x540
	v_cndmask_b32_e32 v164, v164, v165, vcc
	v_add_u32_e32 v196, v196, v164
	s_mov_b32 s0, 557056
	v_mul_lo_u32 v197, s0, v161
	v_add_u32_e32 v197, v197, v163
	v_mov_b32_e32 v164, 0x1852d000
	v_mov_b32_e32 v165, 0x16edd000
	v_cndmask_b32_e32 v164, v164, v165, vcc
	v_add_u32_e32 v197, v197, v164
	v_mov_b32_e32 v164, 1114112
	v_mov_b32_e32 v165, 3342336
	v_cndmask_b32_e32 v198, v164, v165, vcc
	v_mov_b32_e32 v164, 1.0
	v_mov_b32_e32 v165, 0x3e38aa3b
	v_cndmask_b32_e32 v209, v164, v165, vcc
	v_and_b32_e32 v164, 2, v162
	v_cmp_eq_u32_e32 vcc, 0, v164
	v_mov_b32_e32 v164, 1.0
	v_mov_b32_e32 v165, -1.0
	v_cndmask_b32_e32 v207, v164, v165, vcc
	v_and_b32_e32 v164, 1, v162
	v_lshlrev_b32_e32 v205, 5, v164
	v_add_u32_e32 v205, 0x1000, v205
	v_lshlrev_b32_e32 v199, 4, v160
	v_add_u32_e32 v200, 0x440, v199
	v_lshrrev_b32_e32 v164, 3, v160
	v_mul_lo_u32 v201, s0, v164
	v_add_u32_e32 v201, v201, v163
	v_add_u32_e32 v201, 0x190dd000, v201
	v_mov_b32_e32 v216, 1114112
	v_and_b32_e32 v164, 3, v160
	v_lshlrev_b32_e32 v165, 4, v164
	v_add_u32_e32 v202, 0x300, v165
	v_lshrrev_b32_e32 v166, 2, v160
	s_mov_b32 s1, 835584
	v_mul_lo_u32 v203, s1, v166
	v_add_u32_e32 v203, v203, v165
	v_add_u32_e32 v203, 0x12f1d080, v203
	v_mov_b32_e32 v204, 5013504
	v_cmp_lt_u32_e64 s[70:71], 1, v164
	v_and_b32_e32 v166, 1, v164
	v_cmp_eq_u32_e32 vcc, 0, v166
	v_mov_b32_e32 v166, 1.0
	v_mov_b32_e32 v167, -1.0
	v_cndmask_b32_e32 v208, v166, v167, vcc
	s_lshl_b32 s0, s74, 8
	v_lshlrev_b32_e32 v164, 5, v162
	v_add_u32_e32 v164, s0, v164
	v_readlane_b32 s8, v253, 26
	v_readlane_b32 s9, v253, 27
	s_nop 4
	s_mov_b64 exec, s[22:23]
	global_load_dwordx4 v[188:191], v164, s[8:9]
	global_load_dwordx4 v[192:195], v164, s[8:9] offset:16
	s_mov_b64 exec, s[20:21]
	v_readlane_b32 s8, v253, 28
	v_readlane_b32 s9, v253, 29
	s_nop 4
	s_mov_b64 exec, s[26:27]
	global_load_dwordx4 v[188:191], v164, s[8:9]
	global_load_dwordx4 v[192:195], v164, s[8:9] offset:16
	s_mov_b64 exec, s[20:21]
	v_readfirstlane_b32 s0, v143
	s_lshr_b32 s0, s0, 6
	v_readlane_b32 s4, v253, 0
	s_lshl_b32 s4, s4, 3
	s_add_i32 s4, s4, s0
	v_readlane_b32 s5, v255, 23
	s_lshl_b32 s5, s5, 3
	s_waitcnt vmcnt(0)
	s_cmp_ge_u32 s4, 34816
	s_cbranch_scc1 .Lrw_done
	s_mul_i32 s0, s4, 5184
	s_add_u32 s0, s0, 0x5cbd000
	s_add_u32 s10, s50, s0
	s_addc_u32 s11, s51, 0
	s_and_b32 s1, s4, 0xfff
	s_lshr_b32 s7, s1, 6
	s_and_b32 s19, s1, 63
	global_load_dwordx4 v[0:3], v196, s[10:11] nt
	global_load_dwordx4 v[4:7], v199, s[10:11]
	global_load_dwordx4 v[12:15], v200, s[10:11] nt
	global_load_dwordx4 v[16:19], v202, s[10:11]
	v_mov_b32_e32 v212, s19
	v_mov_b32_e32 v213, s7
	v_cndmask_b32_e64 v212, v212, v213, s[100:101]
	v_lshl_add_u32 v212, v212, 6, v205
	v_add_u32_e32 v213, 0x1000, v212
	global_load_dwordx4 v[20:23], v212, s[82:83]
	global_load_dwordx4 v[24:27], v212, s[82:83] offset:16
	global_load_dwordx4 v[28:31], v213, s[82:83]
	global_load_dwordx4 v[32:35], v213, s[82:83] offset:16
	v_mov_b32_e32 v212, s7
	v_mov_b32_e32 v213, s19
	v_cndmask_b32_e64 v212, v212, v213, s[70:71]
	v_lshlrev_b32_e32 v212, 5, v212
	global_load_dwordx4 v[36:39], v212, s[82:83]
	global_load_dwordx4 v[40:43], v212, s[82:83] offset:16
	global_load_dwordx4 v[44:47], v212, s[82:83] offset:2048
	global_load_dwordx4 v[48:51], v212, s[82:83] offset:2064
	global_load_dword v217, v199, s[10:11]
	global_load_dword v218, v199, s[10:11]
	global_load_dword v219, v199, s[10:11]
	global_load_dword v220, v199, s[10:11]
.Lrw_loop:
	s_add_u32 s18, s4, s5
	s_min_u32 s17, s18, 34815
	s_mul_i32 s0, s17, 5184
	s_add_u32 s0, s0, 0x5cbd000
	s_add_u32 s10, s50, s0
	s_addc_u32 s11, s51, 0
	s_and_b32 s1, s17, 0xfff
	s_lshr_b32 s7, s1, 6
	s_and_b32 s19, s1, 63
	global_load_dwordx4 v[52:55], v196, s[10:11] nt
	global_load_dwordx4 v[56:59], v199, s[10:11]
	global_load_dwordx4 v[60:63], v200, s[10:11] nt
	global_load_dwordx4 v[64:67], v202, s[10:11]
	v_mov_b32_e32 v212, s19
	v_mov_b32_e32 v213, s7
	v_cndmask_b32_e64 v212, v212, v213, s[100:101]
	v_lshl_add_u32 v212, v212, 6, v205
	v_add_u32_e32 v213, 0x1000, v212
	global_load_dwordx4 v[96:99], v212, s[82:83]
	global_load_dwordx4 v[100:103], v212, s[82:83] offset:16
	global_load_dwordx4 v[104:107], v213, s[82:83]
	global_load_dwordx4 v[108:111], v213, s[82:83] offset:16
	v_mov_b32_e32 v212, s7
	v_mov_b32_e32 v213, s19
	v_cndmask_b32_e64 v212, v212, v213, s[70:71]
	v_lshlrev_b32_e32 v212, 5, v212
	global_load_dwordx4 v[112:115], v212, s[82:83]
	global_load_dwordx4 v[116:119], v212, s[82:83] offset:16
	global_load_dwordx4 v[120:123], v212, s[82:83] offset:2048
	global_load_dwordx4 v[124:127], v212, s[82:83] offset:2064
	s_lshr_b32 s12, s4, 12
	s_and_b32 s13, s4, 0xfff
	s_mov_b32 s14, 1
	s_cmp_lt_u32 s4, 0x8000
	s_cbranch_scc1 .Lrw_r0_lat
	s_sub_i32 s12, s4, 0x8000
	s_and_b32 s13, s12, 0xff
	s_add_i32 s13, s13, 0x1000
	s_lshr_b32 s12, s12, 8
	s_mov_b32 s14, 0

.Lrw_r0_nokr:
	v_cvt_pk_bf16_f32 v172, v144, v145
	v_cvt_pk_bf16_f32 v173, v146, v147
	v_cvt_pk_bf16_f32 v174, v148, v149
	v_cvt_pk_bf16_f32 v175, v150, v151
	v_mul_lo_u32 v160, s12, v204
	s_mul_i32 s0, s13, 192
	v_add3_u32 v160, v160, v203, s0
	s_mov_b64 exec, s[78:79]
	global_store_dwordx4 v160, v[172:175], s[50:51]
	s_mov_b64 exec, s[20:21]
	s_nop 1
	s_mov_b32 s4, s18
	s_cmp_ge_u32 s4, 34816
	s_cbranch_scc1 .Lrw_done
	s_add_u32 s18, s4, s5
	s_min_u32 s17, s18, 34815
	s_mul_i32 s0, s17, 5184
	s_add_u32 s0, s0, 0x5cbd000
	s_add_u32 s10, s50, s0
	s_addc_u32 s11, s51, 0
	s_and_b32 s1, s17, 0xfff
	s_lshr_b32 s7, s1, 6
	s_and_b32 s19, s1, 63
	global_load_dwordx4 v[0:3], v196, s[10:11] nt
	global_load_dwordx4 v[4:7], v199, s[10:11]
	global_load_dwordx4 v[12:15], v200, s[10:11] nt
	global_load_dwordx4 v[16:19], v202, s[10:11]
	v_mov_b32_e32 v212, s19
	v_mov_b32_e32 v213, s7
	v_cndmask_b32_e64 v212, v212, v213, s[100:101]
	v_lshl_add_u32 v212, v212, 6, v205
	v_add_u32_e32 v213, 0x1000, v212
	global_load_dwordx4 v[20:23], v212, s[82:83]
	global_load_dwordx4 v[24:27], v212, s[82:83] offset:16
	global_load_dwordx4 v[28:31], v213, s[82:83]
	global_load_dwordx4 v[32:35], v213, s[82:83] offset:16
	v_mov_b32_e32 v212, s7
	v_mov_b32_e32 v213, s19
	v_cndmask_b32_e64 v212, v212, v213, s[70:71]
	v_lshlrev_b32_e32 v212, 5, v212
	global_load_dwordx4 v[36:39], v212, s[82:83]
	global_load_dwordx4 v[40:43], v212, s[82:83] offset:16
	global_load_dwordx4 v[44:47], v212, s[82:83] offset:2048
	global_load_dwordx4 v[48:51], v212, s[82:83] offset:2064
	s_lshr_b32 s12, s4, 12
	s_and_b32 s13, s4, 0xfff
	s_mov_b32 s14, 1
	s_cmp_lt_u32 s4, 0x8000
	s_cbranch_scc1 .Lrw_r1_lat
	s_sub_i32 s12, s4, 0x8000
	s_and_b32 s13, s12, 0xff
	s_add_i32 s13, s13, 0x1000
	s_lshr_b32 s12, s12, 8
	s_mov_b32 s14, 0

.LBB0_1254:
	s_or_b64 exec, exec, s[0:1]
	s_waitcnt vmcnt(2)
	v_lshlrev_b32_e32 v138, 16, v98
	v_and_b32_e32 v139, 0xffff0000, v98
	v_lshlrev_b32_e32 v152, 16, v96
	v_and_b32_e32 v153, 0xffff0000, v96
	v_pk_fma_f32 v[36:37], v[12:13], v[138:139], v[36:37]
	v_lshlrev_b32_e32 v138, 16, v99
	v_and_b32_e32 v139, 0xffff0000, v99
	v_pk_fma_f32 v[32:33], v[8:9], v[152:153], v[32:33]
	v_lshlrev_b32_e32 v154, 16, v97
	v_and_b32_e32 v155, 0xffff0000, v97
	v_pk_fma_f32 v[38:39], v[14:15], v[138:139], v[38:39]
	v_pk_mul_f32 v[138:139], v[36:37], v[36:37]
	v_pk_mul_f32 v[152:153], v[32:33], v[32:33]
	v_pk_fma_f32 v[34:35], v[10:11], v[154:155], v[34:35]
	v_pk_mul_f32 v[142:143], v[38:39], v[38:39]
	s_waitcnt vmcnt(1)
	v_lshlrev_b32_e32 v144, 16, v100
	v_and_b32_e32 v145, 0xffff0000, v100
	v_pk_mul_f32 v[154:155], v[34:35], v[34:35]
	v_add_f32_e32 v133, v152, v153
	v_add_f32_e32 v137, v138, v139
	v_pk_fma_f32 v[40:41], v[24:25], v[144:145], v[40:41]
	v_lshlrev_b32_e32 v144, 16, v101
	v_and_b32_e32 v145, 0xffff0000, v101
	v_add_f32_e32 v133, v154, v133
	v_add_f32_e32 v137, v142, v137
	v_pk_fma_f32 v[42:43], v[26:27], v[144:145], v[42:43]
	v_pk_mul_f32 v[144:145], v[40:41], v[40:41]
	v_add_f32_e32 v133, v155, v133
	v_add_f32_e32 v137, v143, v137
	v_pk_mul_f32 v[146:147], v[42:43], v[42:43]
	s_waitcnt vmcnt(0)
	v_lshlrev_b32_e32 v148, 16, v102
	v_and_b32_e32 v149, 0xffff0000, v102
	v_add_f32_e32 v133, v137, v133
	v_add_f32_e32 v137, v144, v145
	v_pk_fma_f32 v[44:45], v[28:29], v[148:149], v[44:45]
	v_lshlrev_b32_e32 v148, 16, v103
	v_and_b32_e32 v149, 0xffff0000, v103
	v_add_f32_e32 v137, v146, v137
	v_pk_fma_f32 v[46:47], v[30:31], v[148:149], v[46:47]
	v_pk_mul_f32 v[148:149], v[44:45], v[44:45]
	v_add_f32_e32 v137, v147, v137
	v_pk_mul_f32 v[150:151], v[46:47], v[46:47]
	v_add_f32_e32 v133, v137, v133
	v_add_f32_e32 v137, v148, v149
	v_add_f32_e32 v137, v150, v137
	v_add_f32_e32 v137, v151, v137
	v_add_f32_e32 v133, v137, v133
	ds_swizzle_b32 v137, v133 offset:swizzle(SWAP,1)
	s_waitcnt lgkmcnt(0)
	v_add_f32_e32 v133, v133, v137
	ds_swizzle_b32 v137, v133 offset:swizzle(SWAP,2)
	s_waitcnt lgkmcnt(0)
	v_add_f32_e32 v133, v133, v137
	ds_swizzle_b32 v137, v133 offset:swizzle(SWAP,4)
	s_waitcnt lgkmcnt(0)
	v_add_f32_e32 v133, v133, v137
	ds_swizzle_b32 v137, v133 offset:swizzle(SWAP,8)
	s_waitcnt lgkmcnt(0)
	v_add_f32_e32 v133, v133, v137
	ds_swizzle_b32 v137, v133 offset:swizzle(SWAP,16)
	s_waitcnt lgkmcnt(0)
	v_add_f32_e32 v133, v133, v137
	v_mov_b32_e32 v137, v133
	s_nop 1
	v_permlane32_swap_b32_e32 v133, v137
	v_add_f32_e32 v133, v133, v137
	v_fmamk_f32 v133, v133, 0x3a800000, v140
	v_mul_f32_e32 v137, 0x4b800000, v133
	v_cmp_gt_f32_e64 s[0:1], s11, v133
	s_nop 1
	v_cndmask_b32_e64 v133, v133, v137, s[0:1]
	v_rsq_f32_e32 v137, v133
	v_ashrrev_i32_e32 v133, 31, v132
	v_lshlrev_b64 v[138:139], 12, v[132:133]
	v_lshl_add_u64 v[138:139], v[112:113], 0, v[138:139]
	v_mul_f32_e32 v133, 0x45800000, v137
	v_cndmask_b32_e64 v146, v137, v133, s[0:1]
	v_pk_mul_f32 v[142:143], v[32:33], v[146:147] op_sel_hi:[1,0]
	v_pk_mul_f32 v[144:145], v[34:35], v[146:147] op_sel_hi:[1,0]
	v_pk_mul_f32 v[142:143], v[0:1], v[142:143]
	v_pk_mul_f32 v[144:145], v[2:3], v[144:145]
	global_store_dwordx4 v[138:139], v[142:145], off nt
	v_readlane_b32 s0, v253, 40
	s_nop 0
	v_pk_mul_f32 v[142:143], v[36:37], v[146:147] op_sel_hi:[1,0]
	v_pk_mul_f32 v[144:145], v[38:39], v[146:147] op_sel_hi:[1,0]
	v_pk_mul_f32 v[142:143], v[4:5], v[142:143]
	v_pk_mul_f32 v[144:145], v[6:7], v[144:145]
	global_store_dwordx4 v[138:139], v[142:145], off offset:1024 nt
	s_nop 1
	v_pk_mul_f32 v[142:143], v[40:41], v[146:147] op_sel_hi:[1,0]
	v_pk_mul_f32 v[144:145], v[42:43], v[146:147] op_sel_hi:[1,0]
	v_pk_mul_f32 v[142:143], v[16:17], v[142:143]
	v_pk_mul_f32 v[144:145], v[18:19], v[144:145]
	global_store_dwordx4 v[138:139], v[142:145], off offset:2048 nt
	s_nop 1
	v_pk_mul_f32 v[142:143], v[44:45], v[146:147] op_sel_hi:[1,0]
	v_pk_mul_f32 v[144:145], v[46:47], v[146:147] op_sel_hi:[1,0]
	v_pk_mul_f32 v[142:143], v[20:21], v[142:143]
	v_pk_mul_f32 v[144:145], v[22:23], v[144:145]
	global_store_dwordx4 v[138:139], v[142:145], off offset:3072 nt
	v_add_u32_e32 v138, s0, v132
	v_cmp_gt_i32_e64 s[0:1], s10, v138
	s_and_saveexec_b64 s[4:5], s[0:1]
	s_cbranch_execz .LBB0_1256
	v_lshlrev_b32_e32 v142, 16, v106
	v_and_b32_e32 v143, 0xffff0000, v106
	v_lshlrev_b32_e32 v154, 16, v104
	v_and_b32_e32 v155, 0xffff0000, v104
	v_pk_fma_f32 v[52:53], v[12:13], v[142:143], v[52:53]
	v_lshlrev_b32_e32 v142, 16, v107
	v_and_b32_e32 v143, 0xffff0000, v107
	v_pk_fma_f32 v[48:49], v[8:9], v[154:155], v[48:49]
	v_lshlrev_b32_e32 v156, 16, v105
	v_and_b32_e32 v157, 0xffff0000, v105
	v_pk_fma_f32 v[54:55], v[14:15], v[142:143], v[54:55]
	v_pk_mul_f32 v[142:143], v[52:53], v[52:53]
	v_pk_mul_f32 v[154:155], v[48:49], v[48:49]
	v_pk_fma_f32 v[50:51], v[10:11], v[156:157], v[50:51]
	v_pk_mul_f32 v[144:145], v[54:55], v[54:55]
	v_lshlrev_b32_e32 v146, 16, v108
	v_and_b32_e32 v147, 0xffff0000, v108
	v_pk_mul_f32 v[156:157], v[50:51], v[50:51]
	v_add_f32_e32 v133, v154, v155
	v_add_f32_e32 v137, v142, v143
	v_pk_fma_f32 v[56:57], v[24:25], v[146:147], v[56:57]
	v_lshlrev_b32_e32 v146, 16, v109
	v_and_b32_e32 v147, 0xffff0000, v109
	v_add_f32_e32 v133, v156, v133
	v_add_f32_e32 v137, v144, v137
	v_pk_fma_f32 v[58:59], v[26:27], v[146:147], v[58:59]
	v_pk_mul_f32 v[146:147], v[56:57], v[56:57]
	v_add_f32_e32 v133, v157, v133
	v_add_f32_e32 v137, v145, v137
	v_pk_mul_f32 v[148:149], v[58:59], v[58:59]
	v_lshlrev_b32_e32 v150, 16, v110
	v_and_b32_e32 v151, 0xffff0000, v110
	v_add_f32_e32 v133, v137, v133
	v_add_f32_e32 v137, v146, v147
	v_pk_fma_f32 v[60:61], v[28:29], v[150:151], v[60:61]
	v_lshlrev_b32_e32 v150, 16, v111
	v_and_b32_e32 v151, 0xffff0000, v111
	v_add_f32_e32 v137, v148, v137
	v_pk_fma_f32 v[62:63], v[30:31], v[150:151], v[62:63]
	v_pk_mul_f32 v[150:151], v[60:61], v[60:61]
	v_add_f32_e32 v137, v149, v137
	v_pk_mul_f32 v[152:153], v[62:63], v[62:63]
	v_add_f32_e32 v133, v137, v133
	v_add_f32_e32 v137, v150, v151
	v_add_f32_e32 v137, v152, v137
	v_add_f32_e32 v137, v153, v137
	v_add_f32_e32 v133, v137, v133
	ds_swizzle_b32 v137, v133 offset:swizzle(SWAP,1)
	v_ashrrev_i32_e32 v139, 31, v138
	v_lshlrev_b64 v[138:139], 12, v[138:139]
	v_lshl_add_u64 v[138:139], v[112:113], 0, v[138:139]
	s_waitcnt lgkmcnt(0)
	v_add_f32_e32 v133, v133, v137
	ds_swizzle_b32 v137, v133 offset:swizzle(SWAP,2)
	s_waitcnt lgkmcnt(0)
	v_add_f32_e32 v133, v133, v137
	ds_swizzle_b32 v137, v133 offset:swizzle(SWAP,4)
	s_waitcnt lgkmcnt(0)
	v_add_f32_e32 v133, v133, v137
	ds_swizzle_b32 v137, v133 offset:swizzle(SWAP,8)
	s_waitcnt lgkmcnt(0)
	v_add_f32_e32 v133, v133, v137
	ds_swizzle_b32 v137, v133 offset:swizzle(SWAP,16)
	s_waitcnt lgkmcnt(0)
	v_add_f32_e32 v133, v133, v137
	v_mov_b32_e32 v137, v133
	s_nop 1
	v_permlane32_swap_b32_e32 v133, v137
	v_add_f32_e32 v133, v133, v137
	v_fmamk_f32 v133, v133, 0x3a800000, v140
	v_mul_f32_e32 v137, 0x4b800000, v133
	v_cmp_gt_f32_e64 s[0:1], s11, v133
	s_nop 1
	v_cndmask_b32_e64 v133, v133, v137, s[0:1]
	v_rsq_f32_e32 v133, v133
	s_nop 0
	v_mul_f32_e32 v137, 0x45800000, v133
	v_cndmask_b32_e64 v146, v133, v137, s[0:1]
	v_pk_mul_f32 v[142:143], v[48:49], v[146:147] op_sel_hi:[1,0]
	v_pk_mul_f32 v[144:145], v[50:51], v[146:147] op_sel_hi:[1,0]
	v_pk_mul_f32 v[142:143], v[0:1], v[142:143]
	v_pk_mul_f32 v[144:145], v[2:3], v[144:145]
	global_store_dwordx4 v[138:139], v[142:145], off nt
	s_nop 1
	v_pk_mul_f32 v[142:143], v[52:53], v[146:147] op_sel_hi:[1,0]
	v_pk_mul_f32 v[144:145], v[54:55], v[146:147] op_sel_hi:[1,0]
	v_pk_mul_f32 v[142:143], v[4:5], v[142:143]
	v_pk_mul_f32 v[144:145], v[6:7], v[144:145]
	global_store_dwordx4 v[138:139], v[142:145], off offset:1024 nt
	s_nop 1
	v_pk_mul_f32 v[142:143], v[56:57], v[146:147] op_sel_hi:[1,0]
	v_pk_mul_f32 v[144:145], v[58:59], v[146:147] op_sel_hi:[1,0]
	v_pk_mul_f32 v[142:143], v[16:17], v[142:143]
	v_pk_mul_f32 v[144:145], v[18:19], v[144:145]
	global_store_dwordx4 v[138:139], v[142:145], off offset:2048 nt
	s_nop 1
	v_pk_mul_f32 v[142:143], v[60:61], v[146:147] op_sel_hi:[1,0]
	v_pk_mul_f32 v[144:145], v[62:63], v[146:147] op_sel_hi:[1,0]
	v_pk_mul_f32 v[142:143], v[20:21], v[142:143]
	v_pk_mul_f32 v[144:145], v[22:23], v[144:145]
	global_store_dwordx4 v[138:139], v[142:145], off offset:3072 nt

.LBB0_1261:
	s_or_b64 exec, exec, s[6:7]
	v_lshlrev_b32_e32 v132, 16, v128
	v_and_b32_e32 v133, 0xffff0000, v128
	v_lshlrev_b32_e32 v150, 16, v130
	v_and_b32_e32 v151, 0xffff0000, v130
	v_pk_fma_f32 v[68:69], v[12:13], v[132:133], v[68:69]
	v_lshlrev_b32_e32 v132, 16, v129
	v_and_b32_e32 v133, 0xffff0000, v129
	v_lshlrev_b32_e32 v142, 16, v126
	v_and_b32_e32 v143, 0xffff0000, v126
	v_pk_fma_f32 v[64:65], v[8:9], v[150:151], v[64:65]
	v_lshlrev_b32_e32 v152, 16, v131
	v_and_b32_e32 v153, 0xffff0000, v131
	v_pk_fma_f32 v[70:71], v[14:15], v[132:133], v[70:71]
	v_pk_mul_f32 v[132:133], v[68:69], v[68:69]
	v_pk_fma_f32 v[72:73], v[24:25], v[142:143], v[72:73]
	v_lshlrev_b32_e32 v142, 16, v127
	v_and_b32_e32 v143, 0xffff0000, v127
	v_pk_mul_f32 v[150:151], v[64:65], v[64:65]
	v_pk_fma_f32 v[66:67], v[10:11], v[152:153], v[66:67]
	v_pk_mul_f32 v[138:139], v[70:71], v[70:71]
	v_pk_fma_f32 v[74:75], v[26:27], v[142:143], v[74:75]
	v_pk_mul_f32 v[142:143], v[72:73], v[72:73]
	v_pk_mul_f32 v[152:153], v[66:67], v[66:67]
	v_add_f32_e32 v137, v150, v151
	v_add_f32_e32 v132, v132, v133
	v_pk_mul_f32 v[144:145], v[74:75], v[74:75]
	v_lshlrev_b32_e32 v146, 16, v124
	v_and_b32_e32 v147, 0xffff0000, v124
	v_add_f32_e32 v137, v152, v137
	v_add_f32_e32 v132, v138, v132
	v_add_f32_e32 v133, v142, v143
	v_pk_fma_f32 v[76:77], v[28:29], v[146:147], v[76:77]
	v_lshlrev_b32_e32 v146, 16, v125
	v_and_b32_e32 v147, 0xffff0000, v125
	v_add_f32_e32 v137, v153, v137
	v_add_f32_e32 v132, v139, v132
	v_add_f32_e32 v133, v144, v133
	v_pk_fma_f32 v[78:79], v[30:31], v[146:147], v[78:79]
	v_pk_mul_f32 v[146:147], v[76:77], v[76:77]
	v_add_f32_e32 v132, v132, v137
	v_add_f32_e32 v133, v145, v133
	v_pk_mul_f32 v[148:149], v[78:79], v[78:79]
	v_add_f32_e32 v132, v133, v132
	v_add_f32_e32 v133, v146, v147
	v_add_f32_e32 v133, v148, v133
	v_add_f32_e32 v133, v149, v133
	v_add_f32_e32 v132, v133, v132
	ds_swizzle_b32 v133, v132 offset:swizzle(SWAP,1)
	s_waitcnt lgkmcnt(0)
	v_add_f32_e32 v132, v132, v133
	ds_swizzle_b32 v133, v132 offset:swizzle(SWAP,2)
	s_waitcnt lgkmcnt(0)
	v_add_f32_e32 v132, v132, v133
	ds_swizzle_b32 v133, v132 offset:swizzle(SWAP,4)
	s_waitcnt lgkmcnt(0)
	v_add_f32_e32 v132, v132, v133
	ds_swizzle_b32 v133, v132 offset:swizzle(SWAP,8)
	s_waitcnt lgkmcnt(0)
	v_add_f32_e32 v132, v132, v133
	ds_swizzle_b32 v133, v132 offset:swizzle(SWAP,16)
	s_waitcnt lgkmcnt(0)
	v_add_f32_e32 v132, v132, v133
	v_mov_b32_e32 v133, v132
	s_nop 1
	v_permlane32_swap_b32_e32 v132, v133
	v_add_f32_e32 v132, v132, v133
	v_fmamk_f32 v132, v132, 0x3a800000, v140
	v_mul_f32_e32 v133, 0x4b800000, v132
	v_cmp_gt_f32_e64 s[0:1], s11, v132
	s_nop 1
	v_cndmask_b32_e64 v132, v132, v133, s[0:1]
	v_rsq_f32_e32 v137, v132
	v_lshlrev_b64 v[132:133], 12, v[134:135]
	v_lshl_add_u64 v[132:133], v[112:113], 0, v[132:133]
	v_mul_f32_e32 v135, 0x45800000, v137
	v_cndmask_b32_e64 v138, v137, v135, s[0:1]
	v_pk_mul_f32 v[142:143], v[64:65], v[138:139] op_sel_hi:[1,0]
	v_pk_mul_f32 v[144:145], v[66:67], v[138:139] op_sel_hi:[1,0]
	v_pk_mul_f32 v[142:143], v[0:1], v[142:143]
	v_pk_mul_f32 v[144:145], v[2:3], v[144:145]
	global_store_dwordx4 v[132:133], v[142:145], off nt
	s_nop 1
	v_pk_mul_f32 v[142:143], v[68:69], v[138:139] op_sel_hi:[1,0]
	v_pk_mul_f32 v[144:145], v[70:71], v[138:139] op_sel_hi:[1,0]
	v_pk_mul_f32 v[142:143], v[4:5], v[142:143]
	v_pk_mul_f32 v[144:145], v[6:7], v[144:145]
	global_store_dwordx4 v[132:133], v[142:145], off offset:1024 nt
	s_nop 1
	v_pk_mul_f32 v[142:143], v[72:73], v[138:139] op_sel_hi:[1,0]
	v_pk_mul_f32 v[144:145], v[74:75], v[138:139] op_sel_hi:[1,0]
	v_pk_mul_f32 v[142:143], v[16:17], v[142:143]
	v_pk_mul_f32 v[144:145], v[18:19], v[144:145]
	global_store_dwordx4 v[132:133], v[142:145], off offset:2048 nt
	s_nop 1
	v_pk_mul_f32 v[142:143], v[76:77], v[138:139] op_sel_hi:[1,0]
	v_pk_mul_f32 v[138:139], v[78:79], v[138:139] op_sel_hi:[1,0]
	v_pk_mul_f32 v[142:143], v[20:21], v[142:143]
	v_pk_mul_f32 v[144:145], v[22:23], v[138:139]
	global_store_dwordx4 v[132:133], v[142:145], off offset:3072 nt
	s_and_saveexec_b64 s[0:1], vcc
	s_cbranch_execz .LBB0_1248
	v_lshlrev_b32_e32 v132, 16, v120
	v_and_b32_e32 v133, 0xffff0000, v120
	v_lshlrev_b32_e32 v150, 16, v122
	v_and_b32_e32 v151, 0xffff0000, v122
	v_pk_fma_f32 v[88:89], v[12:13], v[132:133], v[88:89]
	v_lshlrev_b32_e32 v132, 16, v121
	v_and_b32_e32 v133, 0xffff0000, v121
	v_lshlrev_b32_e32 v142, 16, v118
	v_and_b32_e32 v143, 0xffff0000, v118
	v_pk_fma_f32 v[92:93], v[8:9], v[150:151], v[92:93]
	v_lshlrev_b32_e32 v152, 16, v123
	v_and_b32_e32 v153, 0xffff0000, v123
	v_pk_fma_f32 v[90:91], v[14:15], v[132:133], v[90:91]
	v_pk_mul_f32 v[132:133], v[88:89], v[88:89]
	v_pk_fma_f32 v[84:85], v[24:25], v[142:143], v[84:85]
	v_lshlrev_b32_e32 v142, 16, v119
	v_and_b32_e32 v143, 0xffff0000, v119
	v_pk_mul_f32 v[150:151], v[92:93], v[92:93]
	v_pk_fma_f32 v[94:95], v[10:11], v[152:153], v[94:95]
	v_pk_mul_f32 v[138:139], v[90:91], v[90:91]
	v_pk_fma_f32 v[86:87], v[26:27], v[142:143], v[86:87]
	v_pk_mul_f32 v[142:143], v[84:85], v[84:85]
	v_pk_mul_f32 v[152:153], v[94:95], v[94:95]
	v_add_f32_e32 v135, v150, v151
	v_add_f32_e32 v132, v132, v133
	v_pk_mul_f32 v[144:145], v[86:87], v[86:87]
	v_lshlrev_b32_e32 v146, 16, v116
	v_and_b32_e32 v147, 0xffff0000, v116
	v_add_f32_e32 v135, v152, v135
	v_add_f32_e32 v132, v138, v132
	v_add_f32_e32 v133, v142, v143
	v_pk_fma_f32 v[80:81], v[28:29], v[146:147], v[80:81]
	v_lshlrev_b32_e32 v146, 16, v117
	v_and_b32_e32 v147, 0xffff0000, v117
	v_add_f32_e32 v135, v153, v135
	v_add_f32_e32 v132, v139, v132
	v_add_f32_e32 v133, v144, v133
	v_pk_fma_f32 v[82:83], v[30:31], v[146:147], v[82:83]
	v_pk_mul_f32 v[146:147], v[80:81], v[80:81]
	v_add_f32_e32 v132, v132, v135
	v_add_f32_e32 v133, v145, v133
	v_pk_mul_f32 v[148:149], v[82:83], v[82:83]
	v_add_f32_e32 v132, v133, v132
	v_add_f32_e32 v133, v146, v147
	v_add_f32_e32 v133, v148, v133
	v_add_f32_e32 v133, v149, v133
	v_add_f32_e32 v132, v133, v132
	ds_swizzle_b32 v133, v132 offset:swizzle(SWAP,1)
	v_ashrrev_i32_e32 v137, 31, v136
	s_waitcnt lgkmcnt(0)
	v_add_f32_e32 v132, v132, v133
	ds_swizzle_b32 v133, v132 offset:swizzle(SWAP,2)
	s_waitcnt lgkmcnt(0)
	v_add_f32_e32 v132, v132, v133
	ds_swizzle_b32 v133, v132 offset:swizzle(SWAP,4)
	s_waitcnt lgkmcnt(0)
	v_add_f32_e32 v132, v132, v133
	ds_swizzle_b32 v133, v132 offset:swizzle(SWAP,8)
	s_waitcnt lgkmcnt(0)
	v_add_f32_e32 v132, v132, v133
	ds_swizzle_b32 v133, v132 offset:swizzle(SWAP,16)
	s_waitcnt lgkmcnt(0)
	v_add_f32_e32 v132, v132, v133
	v_mov_b32_e32 v133, v132
	s_nop 1
	v_permlane32_swap_b32_e32 v132, v133
	v_add_f32_e32 v132, v132, v133
	v_fmamk_f32 v132, v132, 0x3a800000, v140
	v_mul_f32_e32 v133, 0x4b800000, v132
	v_cmp_gt_f32_e32 vcc, s11, v132
	s_nop 1
	v_cndmask_b32_e32 v132, v132, v133, vcc
	v_rsq_f32_e32 v135, v132
	v_lshlrev_b64 v[132:133], 12, v[136:137]
	v_lshl_add_u64 v[132:133], v[112:113], 0, v[132:133]
	v_mul_f32_e32 v136, 0x45800000, v135
	v_cndmask_b32_e32 v142, v135, v136, vcc
	v_pk_mul_f32 v[136:137], v[92:93], v[142:143] op_sel_hi:[1,0]
	v_pk_mul_f32 v[138:139], v[94:95], v[142:143] op_sel_hi:[1,0]
	v_pk_mul_f32 v[136:137], v[0:1], v[136:137]
	v_pk_mul_f32 v[138:139], v[2:3], v[138:139]
	global_store_dwordx4 v[132:133], v[136:139], off nt
	s_nop 1
	v_pk_mul_f32 v[136:137], v[88:89], v[142:143] op_sel_hi:[1,0]
	v_pk_mul_f32 v[138:139], v[90:91], v[142:143] op_sel_hi:[1,0]
	v_pk_mul_f32 v[136:137], v[4:5], v[136:137]
	v_pk_mul_f32 v[138:139], v[6:7], v[138:139]
	global_store_dwordx4 v[132:133], v[136:139], off offset:1024 nt
	s_nop 1
	v_pk_mul_f32 v[136:137], v[84:85], v[142:143] op_sel_hi:[1,0]
	v_pk_mul_f32 v[138:139], v[86:87], v[142:143] op_sel_hi:[1,0]
	v_pk_mul_f32 v[136:137], v[16:17], v[136:137]
	v_pk_mul_f32 v[138:139], v[18:19], v[138:139]
	global_store_dwordx4 v[132:133], v[136:139], off offset:2048 nt
	s_nop 1
	v_pk_mul_f32 v[136:137], v[80:81], v[142:143] op_sel_hi:[1,0]
	v_pk_mul_f32 v[138:139], v[82:83], v[142:143] op_sel_hi:[1,0]
	v_pk_mul_f32 v[136:137], v[20:21], v[136:137]
	v_pk_mul_f32 v[138:139], v[22:23], v[138:139]
	global_store_dwordx4 v[132:133], v[136:139], off offset:3072 nt
	s_branch .LBB0_1248
